# strategy 7.5 packed-vs-scalar fp32: the 15 v_pk_add_f32 of each attention row-sum tree split into pairs of v_add_f32 (bit-identical)
# speedup vs baseline: 1.0078x; 1.0035x over previous
; __device__ __forceinline__ unsigned cvtpk(float lo, float hi) { unsigned r; asm("v_cvt_pk_bf16_f32 %0, %1, %2" : "=v"(r) : "v"(lo), "v"(hi)); return r; }
; template <bool MASKED>
; __device__ __forceinline__ void softmax_tile(f32x16& s0, f32x16& s1, float& m, float& l, float& alpha, unsigned mlo, unsigned mhi, bf16x8 (&pk)[4]) {
;     ...
;     for (int r = 0; r < 16; ++r) {
;         float p0 = __builtin_amdgcn_exp2f(s0[r] - mn), p1 = __builtin_amdgcn_exp2f(s1[r] - mn);
;         if (MASKED) { if (s0[r] <= -1e29f) p0 = 0.f; if (s1[r] <= -1e29f) p1 = 0.f; }
;         s0[r] = p0; s1[r] = p1; sum += p0 + p1;
;     }
;     l = l * alpha + sum;
; #pragma unroll
;     for (int k2 = 0; k2 < 2; ++k2) {
;         u32x4 a, b;
;         a.x = cvtpk(s0[8 * k2 + 0], s0[8 * k2 + 1]); a.y = cvtpk(s0[8 * k2 + 2], s0[8 * k2 + 3]); a.z = cvtpk(s0[8 * k2 + 4], s0[8 * k2 + 5]); a.w = cvtpk(s0[8 * k2 + 6], s0[8 * k2 + 7]);
;         b.x = cvtpk(s1[8 * k2 + 0], s1[8 * k2 + 1]); b.y = cvtpk(s1[8 * k2 + 2], s1[8 * k2 + 3]); b.z = cvtpk(s1[8 * k2 + 4], s1[8 * k2 + 5]); b.w = cvtpk(s1[8 * k2 + 6], s1[8 * k2 + 7]);
;         pk[k2] = __builtin_bit_cast(bf16x8, a); pk[2 + k2] = __builtin_bit_cast(bf16x8, b);
;     }
.Lm2_cfast:
	v_exp_f32_e32 v82, v82
	v_exp_f32_e32 v83, v83
	v_exp_f32_e32 v84, v84
	v_exp_f32_e32 v85, v85
	v_exp_f32_e32 v86, v86
	v_exp_f32_e32 v87, v87
	v_exp_f32_e32 v88, v88
	v_exp_f32_e32 v89, v89
	v_exp_f32_e32 v90, v90
	v_exp_f32_e32 v91, v91
	v_exp_f32_e32 v92, v92
	v_exp_f32_e32 v93, v93
	v_exp_f32_e32 v94, v94
	v_exp_f32_e32 v95, v95
	v_exp_f32_e32 v96, v96
	v_exp_f32_e32 v97, v97
	v_exp_f32_e32 v66, v66
	v_exp_f32_e32 v67, v67
	v_exp_f32_e32 v68, v68
	v_exp_f32_e32 v69, v69
	v_exp_f32_e32 v70, v70
	v_exp_f32_e32 v71, v71
	v_exp_f32_e32 v72, v72
	v_exp_f32_e32 v73, v73
	v_exp_f32_e32 v74, v74
	v_exp_f32_e32 v75, v75
	v_exp_f32_e32 v76, v76
	v_exp_f32_e32 v77, v77
	v_exp_f32_e32 v78, v78
	v_exp_f32_e32 v79, v79
	v_exp_f32_e32 v80, v80
	v_exp_f32_e32 v81, v81
	v_add_f32_e32 v150, v82, v84
	v_add_f32_e32 v151, v83, v85
	v_add_f32_e32 v152, v86, v88
	v_add_f32_e32 v153, v87, v89
	v_add_f32_e32 v154, v90, v92
	v_add_f32_e32 v155, v91, v93
	v_add_f32_e32 v156, v94, v96
	v_add_f32_e32 v157, v95, v97
	v_add_f32_e32 v158, v66, v68
	v_add_f32_e32 v159, v67, v69
	v_add_f32_e32 v160, v70, v72
	v_add_f32_e32 v161, v71, v73
	v_add_f32_e32 v162, v74, v76
	v_add_f32_e32 v163, v75, v77
	v_add_f32_e32 v164, v78, v80
	v_add_f32_e32 v165, v79, v81
	v_add_f32_e32 v150, v150, v152
	v_add_f32_e32 v151, v151, v153
	v_add_f32_e32 v154, v154, v156
	v_add_f32_e32 v155, v155, v157
	v_add_f32_e32 v158, v158, v160
	v_add_f32_e32 v159, v159, v161
	v_add_f32_e32 v162, v162, v164
	v_add_f32_e32 v163, v163, v165
	v_add_f32_e32 v150, v150, v154
	v_add_f32_e32 v151, v151, v155
	v_add_f32_e32 v158, v158, v162
	v_add_f32_e32 v159, v159, v163
	v_add_f32_e32 v150, v150, v158
	v_add_f32_e32 v151, v151, v159
	v_add_f32_e32 v164, v150, v151
	v_cvt_pk_bf16_f32 v66, v66, v67
	v_cvt_pk_bf16_f32 v67, v68, v69
	v_cvt_pk_bf16_f32 v68, v70, v71
	v_cvt_pk_bf16_f32 v69, v72, v73
	v_cvt_pk_bf16_f32 v70, v74, v75
	v_cvt_pk_bf16_f32 v71, v76, v77
	v_cvt_pk_bf16_f32 v72, v78, v79
	v_cvt_pk_bf16_f32 v73, v80, v81
	v_cvt_pk_bf16_f32 v74, v82, v83
	v_cvt_pk_bf16_f32 v75, v84, v85
	v_cvt_pk_bf16_f32 v76, v86, v87
	v_cvt_pk_bf16_f32 v77, v88, v89
	v_cvt_pk_bf16_f32 v78, v90, v91
	v_cvt_pk_bf16_f32 v79, v92, v93
	v_cvt_pk_bf16_f32 v80, v94, v95
	v_cvt_pk_bf16_f32 v81, v96, v97
	v_fmac_f32_e32 v164, v147, v0
	v_cmp_neq_f32_e32 vcc, 1.0, v0
	s_cbranch_vccz .LBB0_629
	v_pk_mul_f32 v[64:65], v[64:65], v[0:1] op_sel_hi:[1,0]
	v_pk_mul_f32 v[62:63], v[62:63], v[0:1] op_sel_hi:[1,0]
	v_pk_mul_f32 v[60:61], v[60:61], v[0:1] op_sel_hi:[1,0]
	v_pk_mul_f32 v[58:59], v[58:59], v[0:1] op_sel_hi:[1,0]
	v_pk_mul_f32 v[56:57], v[56:57], v[0:1] op_sel_hi:[1,0]
	v_pk_mul_f32 v[54:55], v[54:55], v[0:1] op_sel_hi:[1,0]
	v_pk_mul_f32 v[52:53], v[52:53], v[0:1] op_sel_hi:[1,0]
	v_pk_mul_f32 v[50:51], v[50:51], v[0:1] op_sel_hi:[1,0]
	v_pk_mul_f32 v[48:49], v[48:49], v[0:1] op_sel_hi:[1,0]
	v_pk_mul_f32 v[46:47], v[46:47], v[0:1] op_sel_hi:[1,0]
	v_pk_mul_f32 v[44:45], v[44:45], v[0:1] op_sel_hi:[1,0]
	v_pk_mul_f32 v[42:43], v[42:43], v[0:1] op_sel_hi:[1,0]
	v_pk_mul_f32 v[40:41], v[40:41], v[0:1] op_sel_hi:[1,0]
	v_pk_mul_f32 v[38:39], v[38:39], v[0:1] op_sel_hi:[1,0]
	v_pk_mul_f32 v[36:37], v[36:37], v[0:1] op_sel_hi:[1,0]
	v_pk_mul_f32 v[34:35], v[34:35], v[0:1] op_sel_hi:[1,0]
	v_pk_mul_f32 v[32:33], v[32:33], v[0:1] op_sel_hi:[1,0]
	v_pk_mul_f32 v[30:31], v[30:31], v[0:1] op_sel_hi:[1,0]
	v_pk_mul_f32 v[28:29], v[28:29], v[0:1] op_sel_hi:[1,0]
	v_pk_mul_f32 v[26:27], v[26:27], v[0:1] op_sel_hi:[1,0]
	v_pk_mul_f32 v[24:25], v[24:25], v[0:1] op_sel_hi:[1,0]
	v_pk_mul_f32 v[22:23], v[22:23], v[0:1] op_sel_hi:[1,0]
	v_pk_mul_f32 v[20:21], v[20:21], v[0:1] op_sel_hi:[1,0]
	v_pk_mul_f32 v[18:19], v[18:19], v[0:1] op_sel_hi:[1,0]
	v_pk_mul_f32 v[16:17], v[16:17], v[0:1] op_sel_hi:[1,0]
	v_pk_mul_f32 v[14:15], v[14:15], v[0:1] op_sel_hi:[1,0]
	v_pk_mul_f32 v[12:13], v[12:13], v[0:1] op_sel_hi:[1,0]
	v_pk_mul_f32 v[10:11], v[10:11], v[0:1] op_sel_hi:[1,0]
	v_pk_mul_f32 v[8:9], v[8:9], v[0:1] op_sel_hi:[1,0]
	v_pk_mul_f32 v[6:7], v[6:7], v[0:1] op_sel_hi:[1,0]
	v_pk_mul_f32 v[4:5], v[4:5], v[0:1] op_sel_hi:[1,0]
	v_pk_mul_f32 v[2:3], v[2:3], v[0:1] op_sel_hi:[1,0]

; __device__ __forceinline__ unsigned cvtpk(float lo, float hi) { unsigned r; asm("v_cvt_pk_bf16_f32 %0, %1, %2" : "=v"(r) : "v"(lo), "v"(hi)); return r; }
; template <bool MASKED>
; __device__ __forceinline__ void softmax_tile(f32x16& s0, f32x16& s1, float& m, float& l, float& alpha, unsigned mlo, unsigned mhi, bf16x8 (&pk)[4]) {
;     ...
;     for (int r = 0; r < 16; ++r) {
;         float p0 = __builtin_amdgcn_exp2f(s0[r] - mn), p1 = __builtin_amdgcn_exp2f(s1[r] - mn);
;         if (MASKED) { if (s0[r] <= -1e29f) p0 = 0.f; if (s1[r] <= -1e29f) p1 = 0.f; }
;         s0[r] = p0; s1[r] = p1; sum += p0 + p1;
;     }
;     l = l * alpha + sum;
; #pragma unroll
;     for (int k2 = 0; k2 < 2; ++k2) {
;         u32x4 a, b;
;         a.x = cvtpk(s0[8 * k2 + 0], s0[8 * k2 + 1]); a.y = cvtpk(s0[8 * k2 + 2], s0[8 * k2 + 3]); a.z = cvtpk(s0[8 * k2 + 4], s0[8 * k2 + 5]); a.w = cvtpk(s0[8 * k2 + 6], s0[8 * k2 + 7]);
;         b.x = cvtpk(s1[8 * k2 + 0], s1[8 * k2 + 1]); b.y = cvtpk(s1[8 * k2 + 2], s1[8 * k2 + 3]); b.z = cvtpk(s1[8 * k2 + 4], s1[8 * k2 + 5]); b.w = cvtpk(s1[8 * k2 + 6], s1[8 * k2 + 7]);
;         pk[k2] = __builtin_bit_cast(bf16x8, a); pk[2 + k2] = __builtin_bit_cast(bf16x8, b);
;     }
.Lm1_cfast:
	v_exp_f32_e32 v82, v82
	v_exp_f32_e32 v83, v83
	v_exp_f32_e32 v84, v84
	v_exp_f32_e32 v85, v85
	v_exp_f32_e32 v86, v86
	v_exp_f32_e32 v87, v87
	v_exp_f32_e32 v88, v88
	v_exp_f32_e32 v89, v89
	v_exp_f32_e32 v90, v90
	v_exp_f32_e32 v91, v91
	v_exp_f32_e32 v92, v92
	v_exp_f32_e32 v93, v93
	v_exp_f32_e32 v94, v94
	v_exp_f32_e32 v95, v95
	v_exp_f32_e32 v96, v96
	v_exp_f32_e32 v97, v97
	v_exp_f32_e32 v66, v66
	v_exp_f32_e32 v67, v67
	v_exp_f32_e32 v68, v68
	v_exp_f32_e32 v69, v69
	v_exp_f32_e32 v70, v70
	v_exp_f32_e32 v71, v71
	v_exp_f32_e32 v72, v72
	v_exp_f32_e32 v73, v73
	v_exp_f32_e32 v74, v74
	v_exp_f32_e32 v75, v75
	v_exp_f32_e32 v76, v76
	v_exp_f32_e32 v77, v77
	v_exp_f32_e32 v78, v78
	v_exp_f32_e32 v79, v79
	v_exp_f32_e32 v80, v80
	v_exp_f32_e32 v81, v81
	v_add_f32_e32 v164, v82, v84
	v_add_f32_e32 v165, v83, v85
	v_add_f32_e32 v166, v86, v88
	v_add_f32_e32 v167, v87, v89
	v_add_f32_e32 v168, v90, v92
	v_add_f32_e32 v169, v91, v93
	v_add_f32_e32 v170, v94, v96
	v_add_f32_e32 v171, v95, v97
	v_add_f32_e32 v172, v66, v68
	v_add_f32_e32 v173, v67, v69
	v_add_f32_e32 v174, v70, v72
	v_add_f32_e32 v175, v71, v73
	v_add_f32_e32 v186, v74, v76
	v_add_f32_e32 v187, v75, v77
	v_add_f32_e32 v188, v78, v80
	v_add_f32_e32 v189, v79, v81
	v_add_f32_e32 v164, v164, v166
	v_add_f32_e32 v165, v165, v167
	v_add_f32_e32 v168, v168, v170
	v_add_f32_e32 v169, v169, v171
	v_add_f32_e32 v172, v172, v174
	v_add_f32_e32 v173, v173, v175
	v_add_f32_e32 v186, v186, v188
	v_add_f32_e32 v187, v187, v189
	v_add_f32_e32 v164, v164, v168
	v_add_f32_e32 v165, v165, v169
	v_add_f32_e32 v172, v172, v186
	v_add_f32_e32 v173, v173, v187
	v_add_f32_e32 v164, v164, v172
	v_add_f32_e32 v165, v165, v173
	v_add_f32_e32 v164, v164, v165
	v_cvt_pk_bf16_f32 v66, v66, v67
	v_cvt_pk_bf16_f32 v67, v68, v69
	v_cvt_pk_bf16_f32 v68, v70, v71
	v_cvt_pk_bf16_f32 v69, v72, v73
	v_cvt_pk_bf16_f32 v70, v74, v75
	v_cvt_pk_bf16_f32 v71, v76, v77
	v_cvt_pk_bf16_f32 v72, v78, v79
	v_cvt_pk_bf16_f32 v73, v80, v81
	v_cvt_pk_bf16_f32 v74, v82, v83
	v_cvt_pk_bf16_f32 v75, v84, v85
	v_cvt_pk_bf16_f32 v76, v86, v87
	v_cvt_pk_bf16_f32 v77, v88, v89
	v_cvt_pk_bf16_f32 v78, v90, v91
	v_cvt_pk_bf16_f32 v79, v92, v93
	v_cvt_pk_bf16_f32 v80, v94, v95
	v_cvt_pk_bf16_f32 v81, v96, v97
	v_fmac_f32_e32 v164, v183, v0
	v_mov_b32_e32 v83, v164
	v_mov_b32_e32 v82, v162
	v_cmp_neq_f32_e32 vcc, 1.0, v0
	s_cbranch_vccz .LBB0_1179
	v_pk_mul_f32 v[64:65], v[64:65], v[0:1] op_sel_hi:[1,0]
	v_pk_mul_f32 v[62:63], v[62:63], v[0:1] op_sel_hi:[1,0]
	v_pk_mul_f32 v[60:61], v[60:61], v[0:1] op_sel_hi:[1,0]
	v_pk_mul_f32 v[58:59], v[58:59], v[0:1] op_sel_hi:[1,0]
	v_pk_mul_f32 v[56:57], v[56:57], v[0:1] op_sel_hi:[1,0]
	v_pk_mul_f32 v[54:55], v[54:55], v[0:1] op_sel_hi:[1,0]
	v_pk_mul_f32 v[52:53], v[52:53], v[0:1] op_sel_hi:[1,0]
	v_pk_mul_f32 v[50:51], v[50:51], v[0:1] op_sel_hi:[1,0]
	v_pk_mul_f32 v[48:49], v[48:49], v[0:1] op_sel_hi:[1,0]
	v_pk_mul_f32 v[46:47], v[46:47], v[0:1] op_sel_hi:[1,0]
	v_pk_mul_f32 v[44:45], v[44:45], v[0:1] op_sel_hi:[1,0]
	v_pk_mul_f32 v[42:43], v[42:43], v[0:1] op_sel_hi:[1,0]
	v_pk_mul_f32 v[40:41], v[40:41], v[0:1] op_sel_hi:[1,0]
	v_pk_mul_f32 v[38:39], v[38:39], v[0:1] op_sel_hi:[1,0]
	v_pk_mul_f32 v[36:37], v[36:37], v[0:1] op_sel_hi:[1,0]
	v_pk_mul_f32 v[34:35], v[34:35], v[0:1] op_sel_hi:[1,0]
	v_pk_mul_f32 v[32:33], v[32:33], v[0:1] op_sel_hi:[1,0]
	v_pk_mul_f32 v[30:31], v[30:31], v[0:1] op_sel_hi:[1,0]
	v_pk_mul_f32 v[28:29], v[28:29], v[0:1] op_sel_hi:[1,0]
	v_pk_mul_f32 v[26:27], v[26:27], v[0:1] op_sel_hi:[1,0]
	v_pk_mul_f32 v[24:25], v[24:25], v[0:1] op_sel_hi:[1,0]
	v_pk_mul_f32 v[22:23], v[22:23], v[0:1] op_sel_hi:[1,0]
	v_pk_mul_f32 v[20:21], v[20:21], v[0:1] op_sel_hi:[1,0]
	v_pk_mul_f32 v[18:19], v[18:19], v[0:1] op_sel_hi:[1,0]
	v_pk_mul_f32 v[16:17], v[16:17], v[0:1] op_sel_hi:[1,0]
	v_pk_mul_f32 v[14:15], v[14:15], v[0:1] op_sel_hi:[1,0]
	v_pk_mul_f32 v[12:13], v[12:13], v[0:1] op_sel_hi:[1,0]
	v_pk_mul_f32 v[10:11], v[10:11], v[0:1] op_sel_hi:[1,0]
	v_pk_mul_f32 v[8:9], v[8:9], v[0:1] op_sel_hi:[1,0]
	v_pk_mul_f32 v[6:7], v[6:7], v[0:1] op_sel_hi:[1,0]
	v_pk_mul_f32 v[4:5], v[4:5], v[0:1] op_sel_hi:[1,0]
	v_pk_mul_f32 v[2:3], v[2:3], v[0:1] op_sel_hi:[1,0]

; __device__ __forceinline__ unsigned cvtpk(float lo, float hi) { unsigned r; asm("v_cvt_pk_bf16_f32 %0, %1, %2" : "=v"(r) : "v"(lo), "v"(hi)); return r; }
; template <bool MASKED>
; __device__ __forceinline__ void softmax_tile(f32x16& s0, f32x16& s1, float& m, float& l, float& alpha, unsigned mlo, unsigned mhi, bf16x8 (&pk)[4]) {
;     ...
;     for (int r = 0; r < 16; ++r) {
;         float p0 = __builtin_amdgcn_exp2f(s0[r] - mn), p1 = __builtin_amdgcn_exp2f(s1[r] - mn);
;         if (MASKED) { if (s0[r] <= -1e29f) p0 = 0.f; if (s1[r] <= -1e29f) p1 = 0.f; }
;         s0[r] = p0; s1[r] = p1; sum += p0 + p1;
;     }
;     l = l * alpha + sum;
; #pragma unroll
;     for (int k2 = 0; k2 < 2; ++k2) {
;         u32x4 a, b;
;         a.x = cvtpk(s0[8 * k2 + 0], s0[8 * k2 + 1]); a.y = cvtpk(s0[8 * k2 + 2], s0[8 * k2 + 3]); a.z = cvtpk(s0[8 * k2 + 4], s0[8 * k2 + 5]); a.w = cvtpk(s0[8 * k2 + 6], s0[8 * k2 + 7]);
;         b.x = cvtpk(s1[8 * k2 + 0], s1[8 * k2 + 1]); b.y = cvtpk(s1[8 * k2 + 2], s1[8 * k2 + 3]); b.z = cvtpk(s1[8 * k2 + 4], s1[8 * k2 + 5]); b.w = cvtpk(s1[8 * k2 + 6], s1[8 * k2 + 7]);
;         pk[k2] = __builtin_bit_cast(bf16x8, a); pk[2 + k2] = __builtin_bit_cast(bf16x8, b);
;     }
.Lm0_cfast:
	v_exp_f32_e32 v96, v96
	v_exp_f32_e32 v97, v97
	v_exp_f32_e32 v98, v98
	v_exp_f32_e32 v99, v99
	v_exp_f32_e32 v100, v100
	v_exp_f32_e32 v101, v101
	v_exp_f32_e32 v102, v102
	v_exp_f32_e32 v103, v103
	v_exp_f32_e32 v104, v104
	v_exp_f32_e32 v105, v105
	v_exp_f32_e32 v106, v106
	v_exp_f32_e32 v107, v107
	v_exp_f32_e32 v108, v108
	v_exp_f32_e32 v109, v109
	v_exp_f32_e32 v110, v110
	v_exp_f32_e32 v111, v111
	v_exp_f32_e32 v80, v80
	v_exp_f32_e32 v81, v81
	v_exp_f32_e32 v82, v82
	v_exp_f32_e32 v83, v83
	v_exp_f32_e32 v84, v84
	v_exp_f32_e32 v85, v85
	v_exp_f32_e32 v86, v86
	v_exp_f32_e32 v87, v87
	v_exp_f32_e32 v88, v88
	v_exp_f32_e32 v89, v89
	v_exp_f32_e32 v90, v90
	v_exp_f32_e32 v91, v91
	v_exp_f32_e32 v92, v92
	v_exp_f32_e32 v93, v93
	v_exp_f32_e32 v94, v94
	v_exp_f32_e32 v95, v95
	v_add_f32_e32 v160, v96, v98
	v_add_f32_e32 v161, v97, v99
	v_add_f32_e32 v162, v100, v102
	v_add_f32_e32 v163, v101, v103
	v_add_f32_e32 v164, v104, v106
	v_add_f32_e32 v165, v105, v107
	v_add_f32_e32 v166, v108, v110
	v_add_f32_e32 v167, v109, v111
	v_add_f32_e32 v168, v80, v82
	v_add_f32_e32 v169, v81, v83
	v_add_f32_e32 v170, v84, v86
	v_add_f32_e32 v171, v85, v87
	v_add_f32_e32 v172, v88, v90
	v_add_f32_e32 v173, v89, v91
	v_add_f32_e32 v174, v92, v94
	v_add_f32_e32 v175, v93, v95
	v_add_f32_e32 v160, v160, v162
	v_add_f32_e32 v161, v161, v163
	v_add_f32_e32 v164, v164, v166
	v_add_f32_e32 v165, v165, v167
	v_add_f32_e32 v168, v168, v170
	v_add_f32_e32 v169, v169, v171
	v_add_f32_e32 v172, v172, v174
	v_add_f32_e32 v173, v173, v175
	v_add_f32_e32 v160, v160, v164
	v_add_f32_e32 v161, v161, v165
	v_add_f32_e32 v168, v168, v172
	v_add_f32_e32 v169, v169, v173
	v_add_f32_e32 v160, v160, v168
	v_add_f32_e32 v161, v161, v169
	v_add_f32_e32 v15, v160, v161
	v_cvt_pk_bf16_f32 v2, v80, v81
	v_cvt_pk_bf16_f32 v3, v82, v83
	v_cvt_pk_bf16_f32 v4, v84, v85
	v_cvt_pk_bf16_f32 v5, v86, v87
	v_cvt_pk_bf16_f32 v6, v88, v89
	v_cvt_pk_bf16_f32 v7, v90, v91
	v_cvt_pk_bf16_f32 v8, v92, v93
	v_cvt_pk_bf16_f32 v9, v94, v95
	v_cvt_pk_bf16_f32 v80, v104, v105
	v_cvt_pk_bf16_f32 v81, v106, v107
	v_cvt_pk_bf16_f32 v82, v108, v109
	v_cvt_pk_bf16_f32 v83, v110, v111
	v_cvt_pk_bf16_f32 v10, v96, v97
	v_cvt_pk_bf16_f32 v11, v98, v99
	v_cvt_pk_bf16_f32 v12, v100, v101
	v_cvt_pk_bf16_f32 v13, v102, v103
	v_fmac_f32_e32 v15, v234, v0
	v_cmp_neq_f32_e32 vcc, 1.0, v0
	s_cbranch_vccz .LBB0_1193
	v_pk_mul_f32 v[78:79], v[78:79], v[0:1] op_sel_hi:[1,0]
	v_pk_mul_f32 v[76:77], v[76:77], v[0:1] op_sel_hi:[1,0]
	v_pk_mul_f32 v[74:75], v[74:75], v[0:1] op_sel_hi:[1,0]
	v_pk_mul_f32 v[72:73], v[72:73], v[0:1] op_sel_hi:[1,0]
	v_pk_mul_f32 v[70:71], v[70:71], v[0:1] op_sel_hi:[1,0]
	v_pk_mul_f32 v[68:69], v[68:69], v[0:1] op_sel_hi:[1,0]
	v_pk_mul_f32 v[66:67], v[66:67], v[0:1] op_sel_hi:[1,0]
	v_pk_mul_f32 v[64:65], v[64:65], v[0:1] op_sel_hi:[1,0]
	v_pk_mul_f32 v[62:63], v[62:63], v[0:1] op_sel_hi:[1,0]
	v_pk_mul_f32 v[60:61], v[60:61], v[0:1] op_sel_hi:[1,0]
	v_pk_mul_f32 v[58:59], v[58:59], v[0:1] op_sel_hi:[1,0]
	v_pk_mul_f32 v[56:57], v[56:57], v[0:1] op_sel_hi:[1,0]
	v_pk_mul_f32 v[54:55], v[54:55], v[0:1] op_sel_hi:[1,0]
	v_pk_mul_f32 v[52:53], v[52:53], v[0:1] op_sel_hi:[1,0]
	v_pk_mul_f32 v[50:51], v[50:51], v[0:1] op_sel_hi:[1,0]
	v_pk_mul_f32 v[48:49], v[48:49], v[0:1] op_sel_hi:[1,0]
	v_pk_mul_f32 v[46:47], v[46:47], v[0:1] op_sel_hi:[1,0]
	v_pk_mul_f32 v[44:45], v[44:45], v[0:1] op_sel_hi:[1,0]
	v_pk_mul_f32 v[42:43], v[42:43], v[0:1] op_sel_hi:[1,0]
	v_pk_mul_f32 v[40:41], v[40:41], v[0:1] op_sel_hi:[1,0]
	v_pk_mul_f32 v[38:39], v[38:39], v[0:1] op_sel_hi:[1,0]
	v_pk_mul_f32 v[36:37], v[36:37], v[0:1] op_sel_hi:[1,0]
	v_pk_mul_f32 v[34:35], v[34:35], v[0:1] op_sel_hi:[1,0]
	v_pk_mul_f32 v[32:33], v[32:33], v[0:1] op_sel_hi:[1,0]
	v_pk_mul_f32 v[30:31], v[30:31], v[0:1] op_sel_hi:[1,0]
	v_pk_mul_f32 v[28:29], v[28:29], v[0:1] op_sel_hi:[1,0]
	v_pk_mul_f32 v[26:27], v[26:27], v[0:1] op_sel_hi:[1,0]
	v_pk_mul_f32 v[24:25], v[24:25], v[0:1] op_sel_hi:[1,0]
	v_pk_mul_f32 v[22:23], v[22:23], v[0:1] op_sel_hi:[1,0]
	v_pk_mul_f32 v[20:21], v[20:21], v[0:1] op_sel_hi:[1,0]
	v_pk_mul_f32 v[18:19], v[18:19], v[0:1] op_sel_hi:[1,0]
	v_pk_mul_f32 v[16:17], v[16:17], v[0:1] op_sel_hi:[1,0]
